# sample-attention chunk loop: key-bias load issued first so the V gather stays in flight behind the counted wait; 16-lane row max by DPP instead of 12 ds_bpermute round trips
# baseline (speedup 1.0000x reference)
; __device__ __forceinline__ unsigned pk2(float lo, float hi) { return pg8::cvt_pk_bf16(lo, hi); }
; __device__ __forceinline__ void sample_attn(const Args& a, int j, int bh, unsigned char* ldsb, bool dummy = false) {
;     ...
;     for (int c = 0; c < 17; ++c) {
;         float vr[32];
;         if (c < 16) {
; #pragma unroll
;             for (int q = 0; q < 32; ++q) vr[q] = cv[(size_t)(c * 128 + (q >> 3) * 32 + fq * 8 + (q & 7)) * EB + 16 * wid + fr];
;         } else {
; #pragma unroll
;             for (int q = 0; q < 32; ++q) { const int key = (q >> 3) * 32 + fq * 8 + (q & 7); vr[q] = key < TS ? nv[(size_t)key * EB + 16 * wid + fr] : 0.f; }
;         }
;         const float bias = c < 16 ? cb[c * 128 + kl] : (kl < TS ? cb[PAST + kl] : 0.f);
;         f32x4 sacc = {0.f, 0.f, 0.f, 0.f};
; #pragma unroll
;         for (int kk = 0; kk < 4; ++kk) { const f32x4 x0 = kr[2 * kk], x1 = kr[2 * kk + 1];
;             u32x4 w; w.x = pk2(x0[0], x0[1]); w.y = pk2(x0[2], x0[3]); w.z = pk2(x1[0], x1[1]); w.w = pk2(x1[2], x1[3]);
;             sacc = __builtin_amdgcn_mfma_f32_16x16x32_bf16(qf[kk], __builtin_bit_cast(bf16x8, w), sacc, 0, 0, 0); }
.LBB0_1417:
	global_load_dword v127, v[70:71], off
	v_lshl_add_u64 v[76:77], v[72:73], 0, s[28:29]
	s_movk_i32 s4, 0x2000
	v_add_co_u32_e64 v84, s[4:5], s4, v76
	global_load_dword v69, v[76:77], off
	s_nop 0
	v_addc_co_u32_e64 v85, s[4:5], 0, v77, s[4:5]
	s_movk_i32 s4, 0x4000
	global_load_dword v96, v[84:85], off
	v_add_co_u32_e64 v84, s[4:5], s4, v76
	s_nop 1
	v_addc_co_u32_e64 v85, s[4:5], 0, v77, s[4:5]
	s_movk_i32 s4, 0x6000
	global_load_dword v97, v[84:85], off
	v_add_co_u32_e64 v84, s[4:5], s4, v76
	s_nop 1
	v_addc_co_u32_e64 v85, s[4:5], 0, v77, s[4:5]
	global_load_dword v98, v[84:85], off
	v_add_co_u32_e64 v84, s[4:5], s91, v76
	s_nop 1
	v_addc_co_u32_e64 v85, s[4:5], 0, v77, s[4:5]
	s_mov_b32 s4, 0xa000
	global_load_dword v99, v[84:85], off
	v_add_co_u32_e64 v84, s[4:5], s4, v76
	s_nop 1
	v_addc_co_u32_e64 v85, s[4:5], 0, v77, s[4:5]
	s_mov_b32 s4, 0xc000
	global_load_dword v100, v[84:85], off
	v_add_co_u32_e64 v84, s[4:5], s4, v76
	s_nop 1
	v_addc_co_u32_e64 v85, s[4:5], 0, v77, s[4:5]
	s_mov_b32 s4, 0xe000
	global_load_dword v101, v[84:85], off
	v_add_co_u32_e64 v84, s[4:5], s4, v76
	s_nop 1
	v_addc_co_u32_e64 v85, s[4:5], 0, v77, s[4:5]
	global_load_dword v105, v[84:85], off
	v_add_co_u32_e64 v84, s[4:5], s41, v76
	s_nop 1
	v_addc_co_u32_e64 v85, s[4:5], 0, v77, s[4:5]
	s_mov_b32 s4, 0x42000
	global_load_dword v102, v[84:85], off
	v_add_co_u32_e64 v84, s[4:5], s4, v76
	s_nop 1
	v_addc_co_u32_e64 v85, s[4:5], 0, v77, s[4:5]
	s_mov_b32 s4, 0x44000
	global_load_dword v103, v[84:85], off
	v_add_co_u32_e64 v84, s[4:5], s4, v76
	s_nop 1
	v_addc_co_u32_e64 v85, s[4:5], 0, v77, s[4:5]
	s_mov_b32 s4, 0x46000
	global_load_dword v104, v[84:85], off
	v_add_co_u32_e64 v84, s[4:5], s4, v76
	s_nop 1
	v_addc_co_u32_e64 v85, s[4:5], 0, v77, s[4:5]
	global_load_dword v106, v[84:85], off
	v_add_co_u32_e64 v84, s[4:5], s1, v76
	s_nop 1
	v_addc_co_u32_e64 v85, s[4:5], 0, v77, s[4:5]
	s_mov_b32 s4, 0x4a000
	global_load_dword v107, v[84:85], off
	v_add_co_u32_e64 v84, s[4:5], s4, v76
	s_nop 1
	v_addc_co_u32_e64 v85, s[4:5], 0, v77, s[4:5]
	s_mov_b32 s4, 0x4c000
	global_load_dword v108, v[84:85], off
	v_add_co_u32_e64 v84, s[4:5], s4, v76
	s_nop 1
	v_addc_co_u32_e64 v85, s[4:5], 0, v77, s[4:5]
	s_mov_b32 s4, 0x4e000
	global_load_dword v109, v[84:85], off
	v_add_co_u32_e64 v84, s[4:5], s4, v76
	s_nop 1
	v_addc_co_u32_e64 v85, s[4:5], 0, v77, s[4:5]
	global_load_dword v111, v[84:85], off
	v_add_co_u32_e64 v84, s[4:5], s92, v76
	s_nop 1
	v_addc_co_u32_e64 v85, s[4:5], 0, v77, s[4:5]
	s_mov_b32 s4, 0x82000
	global_load_dword v110, v[84:85], off
	v_add_co_u32_e64 v84, s[4:5], s4, v76
	s_nop 1
	v_addc_co_u32_e64 v85, s[4:5], 0, v77, s[4:5]
	s_mov_b32 s4, 0x84000
	global_load_dword v112, v[84:85], off
	v_add_co_u32_e64 v84, s[4:5], s4, v76
	s_nop 1
	v_addc_co_u32_e64 v85, s[4:5], 0, v77, s[4:5]
	s_mov_b32 s4, 0x86000
	global_load_dword v113, v[84:85], off
	v_add_co_u32_e64 v84, s[4:5], s4, v76
	s_nop 1
	v_addc_co_u32_e64 v85, s[4:5], 0, v77, s[4:5]
	s_mov_b32 s4, 0x88000
	global_load_dword v114, v[84:85], off
	v_add_co_u32_e64 v84, s[4:5], s4, v76
	s_nop 1
	v_addc_co_u32_e64 v85, s[4:5], 0, v77, s[4:5]
	s_mov_b32 s4, 0x8a000
	global_load_dword v115, v[84:85], off
	v_add_co_u32_e64 v84, s[4:5], s4, v76
	s_nop 1
	v_addc_co_u32_e64 v85, s[4:5], 0, v77, s[4:5]
	s_mov_b32 s4, 0x8c000
	global_load_dword v116, v[84:85], off
	v_add_co_u32_e64 v84, s[4:5], s4, v76
	s_nop 1
	v_addc_co_u32_e64 v85, s[4:5], 0, v77, s[4:5]
	s_mov_b32 s4, 0x8e000
	global_load_dword v117, v[84:85], off
	v_add_co_u32_e64 v84, s[4:5], s4, v76
	s_nop 1
	v_addc_co_u32_e64 v85, s[4:5], 0, v77, s[4:5]
	s_mov_b32 s4, 0xc0000
	global_load_dword v122, v[84:85], off
	v_add_co_u32_e64 v84, s[4:5], s4, v76
	s_nop 1
	v_addc_co_u32_e64 v85, s[4:5], 0, v77, s[4:5]
	s_mov_b32 s4, 0xc2000
	global_load_dword v118, v[84:85], off
	v_add_co_u32_e64 v84, s[4:5], s4, v76
	s_nop 1
	v_addc_co_u32_e64 v85, s[4:5], 0, v77, s[4:5]
	s_mov_b32 s4, 0xc4000
	global_load_dword v119, v[84:85], off
	v_add_co_u32_e64 v84, s[4:5], s4, v76
	s_nop 1
	v_addc_co_u32_e64 v85, s[4:5], 0, v77, s[4:5]
	s_mov_b32 s4, 0xc6000
	global_load_dword v120, v[84:85], off
	v_add_co_u32_e64 v84, s[4:5], s4, v76
	s_nop 1
	v_addc_co_u32_e64 v85, s[4:5], 0, v77, s[4:5]
	s_mov_b32 s4, 0xc8000
	global_load_dword v121, v[84:85], off
	v_add_co_u32_e64 v84, s[4:5], s4, v76
	s_nop 1
	v_addc_co_u32_e64 v85, s[4:5], 0, v77, s[4:5]
	s_mov_b32 s4, 0xca000
	global_load_dword v123, v[84:85], off
	v_add_co_u32_e64 v84, s[4:5], s4, v76
	s_nop 1
	v_addc_co_u32_e64 v85, s[4:5], 0, v77, s[4:5]
	s_mov_b32 s4, 0xcc000
	global_load_dword v124, v[84:85], off
	v_add_co_u32_e64 v84, s[4:5], s4, v76
	s_nop 1
	v_addc_co_u32_e64 v85, s[4:5], 0, v77, s[4:5]
	s_mov_b32 s4, 0xce000
	s_nop 0
	v_add_co_u32_e64 v76, s[4:5], s4, v76
	global_load_dword v125, v[84:85], off
	s_nop 0
	v_addc_co_u32_e64 v77, s[4:5], 0, v77, s[4:5]
	global_load_dword v126, v[76:77], off
	s_waitcnt vmcnt(39)
	v_cvt_pk_bf16_f32 v50, v50, v51
	v_cvt_pk_bf16_f32 v51, v52, v53
	v_cvt_pk_bf16_f32 v52, v46, v47
	v_cvt_pk_bf16_f32 v53, v48, v49
	s_waitcnt vmcnt(37)
	v_cvt_pk_bf16_f32 v42, v42, v43
	v_cvt_pk_bf16_f32 v43, v44, v45
	v_cvt_pk_bf16_f32 v44, v38, v39
	v_cvt_pk_bf16_f32 v45, v40, v41
	s_waitcnt vmcnt(35)
	v_cvt_pk_bf16_f32 v34, v34, v35
	v_mfma_f32_16x16x32_bf16 v[46:49], v[14:17], v[50:53], 0
	v_cvt_pk_bf16_f32 v35, v36, v37
	v_cvt_pk_bf16_f32 v36, v30, v31
	v_cvt_pk_bf16_f32 v37, v32, v33
	v_mfma_f32_16x16x32_bf16 v[38:41], v[10:13], v[42:45], v[46:49]
	s_waitcnt vmcnt(33)
; __device__ __forceinline__ void sample_attn(const Args& a, int j, int bh, unsigned char* ldsb, bool dummy = false) {
;     ...
;         if (c + 1 < 16) {
; #pragma unroll
;             for (int q = 0; q < 8; ++q) kr[q] = *(const f32x4*)(ck + (size_t)((c + 1) * 128 + kl) * EB + (q >> 1) * 32 + fq * 8 + (q & 1) * 4);
;         } else if (c + 1 == 16) {
; #pragma unroll
;             for (int q = 0; q < 8; ++q) kr[q] = kl < TS ? *(const f32x4*)(nk + (size_t)kl * EB + (q >> 1) * 32 + fq * 8 + (q & 1) * 4) : (f32x4){0.f, 0.f, 0.f, 0.f};
;         }
;         float s[4], mw[4];
; #pragma unroll
;         for (int r = 0; r < 4; ++r) { s[r] = sacc[r] * att::SCALE + bias; if (c == 16 && (kl >= TS || kl > 4 * fq + r)) s[r] = -__builtin_inff(); mw[r] = s[r]; }
; #pragma unroll
;         for (int o = 1; o < 16; o <<= 1) {
; #pragma unroll
;             for (int r = 0; r < 4; ++r) mw[r] = fmaxf(mw[r], __shfl_xor(mw[r], o)); }
;         if (fr == 0) {
; #pragma unroll
;             for (int r = 0; r < 4; ++r) wmx[buf * 128 + (4 * fq + r) * 8 + wid] = mw[r]; }
;         __syncthreads();
	v_cvt_pk_bf16_f32 v26, v26, v27
	v_cvt_pk_bf16_f32 v27, v28, v29
	v_cvt_pk_bf16_f32 v28, v22, v23
	v_mfma_f32_16x16x32_bf16 v[30:33], v[6:9], v[34:37], v[38:41]
	v_cvt_pk_bf16_f32 v29, v24, v25
	v_cmp_lt_i32_e64 s[4:5], v214, v200
	v_mfma_f32_16x16x32_bf16 v[130:133], v[2:5], v[26:29], v[30:33]
	v_lshl_add_u64 v[26:27], v[74:75], 0, s[28:29]
	s_nop 1
	global_load_dwordx4 v[46:49], v[26:27], off offset:-240
	global_load_dwordx4 v[50:53], v[26:27], off offset:-256
	global_load_dwordx4 v[38:41], v[26:27], off offset:-112
	global_load_dwordx4 v[42:45], v[26:27], off offset:-128
	global_load_dwordx4 v[30:33], v[26:27], off offset:16
	global_load_dwordx4 v[34:37], v[26:27], off
	global_load_dwordx4 v[22:25], v[26:27], off offset:144
	s_nop 0
	global_load_dwordx4 v[26:29], v[26:27], off offset:128
	s_waitcnt vmcnt(40)
	v_fmamk_f32 v130, v130, 0x3db504f3, v127
	v_fmamk_f32 v129, v131, 0x3db504f3, v127
	v_fmamk_f32 v128, v132, 0x3db504f3, v127
	v_fmac_f32_e32 v127, 0x3db504f3, v133
	v_max_f32_dpp v92, v130, v130 quad_perm:[1,0,3,2] row_mask:0xf bank_mask:0xf
	v_max_f32_dpp v131, v129, v129 quad_perm:[1,0,3,2] row_mask:0xf bank_mask:0xf
	v_max_f32_dpp v132, v128, v128 quad_perm:[1,0,3,2] row_mask:0xf bank_mask:0xf
	v_max_f32_dpp v133, v127, v127 quad_perm:[1,0,3,2] row_mask:0xf bank_mask:0xf
	v_max_f32_dpp v92, v92, v92 quad_perm:[2,3,0,1] row_mask:0xf bank_mask:0xf
	v_max_f32_dpp v131, v131, v131 quad_perm:[2,3,0,1] row_mask:0xf bank_mask:0xf
	v_max_f32_dpp v132, v132, v132 quad_perm:[2,3,0,1] row_mask:0xf bank_mask:0xf
	v_max_f32_dpp v133, v133, v133 quad_perm:[2,3,0,1] row_mask:0xf bank_mask:0xf
	v_max_f32_dpp v92, v92, v92 row_ror:4 row_mask:0xf bank_mask:0xf
	v_max_f32_dpp v131, v131, v131 row_ror:4 row_mask:0xf bank_mask:0xf
	v_max_f32_dpp v132, v132, v132 row_ror:4 row_mask:0xf bank_mask:0xf
	v_max_f32_dpp v133, v133, v133 row_ror:4 row_mask:0xf bank_mask:0xf
	v_max_f32_dpp v92, v92, v92 row_ror:8 row_mask:0xf bank_mask:0xf
	v_max_f32_dpp v131, v131, v131 row_ror:8 row_mask:0xf bank_mask:0xf
	v_max_f32_dpp v132, v132, v132 row_ror:8 row_mask:0xf bank_mask:0xf
	v_max_f32_dpp v133, v133, v133 row_ror:8 row_mask:0xf bank_mask:0xf
	s_lshl_b32 s50, s27, 9
	s_mov_b64 s[4:5], exec
	s_andn2_b64 exec, exec, vcc
	v_add_u32_e32 v134, s50, v82
	ds_write2_b32 v134, v92, v131 offset1:8
	ds_write2_b32 v134, v132, v133 offset0:16 offset1:24
	s_mov_b64 exec, s[4:5]
	v_mov_b32_e32 v133, s50
	v_lshlrev_b32_e32 v76, 2, v214
	v_lshlrev_b32_e32 v77, 2, v252
	v_lshlrev_b32_e32 v84, 2, v215
	v_lshlrev_b32_e32 v85, 2, v201
; __device__ __forceinline__ unsigned f2bf(float f) { unsigned u = __builtin_bit_cast(unsigned, f); return (u + 0x7fffu + ((u >> 16) & 1u)) >> 16; }
; __device__ __forceinline__ unsigned pk2(float lo, float hi) { return pg8::cvt_pk_bf16(lo, hi); }
; __device__ __forceinline__ void sample_attn(const Args& a, int j, int bh, unsigned char* ldsb, bool dummy = false) {
;     ...
;         __syncthreads();
;         float p[4];
; #pragma unroll
;         for (int r = 0; r < 4; ++r) { const f32x4 w0 = *(const f32x4*)(wmx + buf * 128 + (4 * fq + r) * 8), w1 = *(const f32x4*)(wmx + buf * 128 + (4 * fq + r) * 8 + 4);
;             const float mc = fmaxf(fmaxf(fmaxf(w0[0], w0[1]), fmaxf(w0[2], w0[3])), fmaxf(fmaxf(w1[0], w1[1]), fmaxf(w1[2], w1[3])));
;             const float mn = fmaxf(m[r], mc), al = __expf(m[r] - mn); m[r] = mn; p[r] = __expf(s[r] - mn); ls[r] = ls[r] * al + p[r]; oacc[r] *= al;
;             Pb[buf * 16 * PP + (4 * fq + r) * PP + kl] = (bf16_t)f2bf(p[r]); }
;         __syncthreads();
; #pragma unroll
;         for (int kk = 0; kk < 4; ++kk) { const bf16x8 pa = *(const bf16x8*)(Pb + buf * 16 * PP + fr * PP + kk * 32 + fq * 8);
;             u32x4 w; w.x = pk2(vr[kk * 8 + 0], vr[kk * 8 + 1]); w.y = pk2(vr[kk * 8 + 2], vr[kk * 8 + 3]); w.z = pk2(vr[kk * 8 + 4], vr[kk * 8 + 5]); w.w = pk2(vr[kk * 8 + 6], vr[kk * 8 + 7]);
;             oacc = __builtin_amdgcn_mfma_f32_16x16x32_bf16(pa, __builtin_bit_cast(bf16x8, w), oacc, 0, 0, 0); }
;         buf ^= 1;
.LBB0_1421:
	s_or_b64 exec, exec, s[4:5]
	v_add_u32_e32 v142, 0, v133
	v_add_u32_e32 v92, v142, v57
	s_waitcnt lgkmcnt(0)
	s_barrier
	ds_read_b128 v[132:135], v92
	ds_read_b128 v[136:139], v92 offset:16
	s_mul_i32 s4, s27, 0x1100
	v_add_u32_e32 v143, s4, v87
	s_xor_b32 s27, s27, 1
	s_waitcnt lgkmcnt(1)
	v_max_f32_e32 v92, v135, v135
	v_max_f32_e32 v131, v134, v134
	v_max_f32_e32 v92, v131, v92
	v_max3_f32 v92, v132, v133, v92
	s_waitcnt lgkmcnt(0)
	v_max_f32_e32 v131, v139, v139
	v_max_f32_e32 v132, v138, v138
	v_max_f32_e32 v131, v132, v131
	v_max3_f32 v131, v136, v137, v131
	v_max3_f32 v92, v95, v92, v131
	v_sub_f32_e32 v95, v95, v92
	v_mul_f32_e32 v95, 0x3fb8aa3b, v95
	v_exp_f32_e32 v138, v95
	v_sub_f32_e32 v95, v130, v92
	v_mul_f32_e32 v95, 0x3fb8aa3b, v95
	v_exp_f32_e32 v140, v95
	v_add_u32_e32 v130, v143, v90
	v_add_u32_e32 v143, v143, v88
	s_add_u32 s28, s28, 0x100000
	v_bfe_u32 v95, v140, 16, 1
	v_add3_u32 v95, v140, v95, s89
	ds_write_b16_d16_hi v130, v95 offset:1024
	v_add_u32_e32 v95, v142, v91
	ds_read_b128 v[130:133], v95
	ds_read_b128 v[134:137], v95 offset:16
	s_addc_u32 s29, s29, 0
	v_lshl_add_u64 v[70:71], v[70:71], 0, s[86:87]
	s_cmp_eq_u32 s28, 0xf00000
	s_waitcnt lgkmcnt(1)
	v_max_f32_e32 v95, v133, v133
	v_max_f32_e32 v132, v132, v132
	v_max_f32_e32 v95, v132, v95
	v_max3_f32 v95, v130, v131, v95
	s_waitcnt lgkmcnt(0)
	v_max_f32_e32 v130, v137, v137
	v_max_f32_e32 v131, v136, v136
	v_max_f32_e32 v130, v131, v130
	v_max3_f32 v130, v134, v135, v130
	v_max3_f32 v95, v93, v95, v130
	v_sub_f32_e32 v93, v93, v95
	v_mul_f32_e32 v93, 0x3fb8aa3b, v93
	v_exp_f32_e32 v139, v93
	v_sub_f32_e32 v93, v129, v95
	v_mul_f32_e32 v93, 0x3fb8aa3b, v93
	v_exp_f32_e32 v141, v93
	v_pk_mul_f32 v[18:19], v[18:19], v[138:139]
	v_bfe_u32 v93, v141, 16, 1
	v_add3_u32 v93, v141, v93, s89
	ds_write_b16_d16_hi v143, v93 offset:1024
	v_add_u32_e32 v93, v142, v89
	ds_read_b128 v[130:133], v93
	ds_read_b128 v[134:137], v93 offset:16
	v_pk_fma_f32 v[62:63], v[62:63], v[138:139], v[140:141]
	s_waitcnt lgkmcnt(1)
	v_max_f32_e32 v93, v133, v133
	v_max_f32_e32 v129, v132, v132
	v_max_f32_e32 v93, v129, v93
	v_max3_f32 v93, v130, v131, v93
	s_waitcnt lgkmcnt(0)
	v_max_f32_e32 v129, v137, v137
	v_max_f32_e32 v130, v136, v136
	v_max_f32_e32 v129, v130, v129
	v_max3_f32 v129, v134, v135, v129
	v_max3_f32 v93, v94, v93, v129
	v_sub_f32_e32 v94, v94, v93
	v_mul_f32_e32 v94, 0x3fb8aa3b, v94
	v_exp_f32_e32 v136, v94
	v_sub_f32_e32 v94, v128, v93
	v_mul_f32_e32 v94, 0x3fb8aa3b, v94
	v_exp_f32_e32 v140, v94
	s_nop 0
	v_bfe_u32 v94, v140, 16, 1
	v_add3_u32 v94, v140, v94, s89
	ds_write_b16_d16_hi v143, v94 offset:1296
	v_add_u32_e32 v94, v142, v86
	ds_read_b128 v[128:131], v94
	ds_read_b128 v[132:135], v94 offset:16
	s_waitcnt lgkmcnt(1)
	v_max_f32_e32 v94, v131, v131
	v_max_f32_e32 v130, v130, v130
	v_max_f32_e32 v94, v130, v94
	v_max3_f32 v94, v128, v129, v94
	s_waitcnt lgkmcnt(0)
	v_max_f32_e32 v128, v135, v135
	v_max_f32_e32 v129, v134, v134
	v_max_f32_e32 v128, v129, v128
	v_max3_f32 v128, v132, v133, v128
	v_max3_f32 v94, v0, v94, v128
	v_sub_f32_e32 v0, v0, v94
	v_mul_f32_e32 v0, 0x3fb8aa3b, v0
	v_exp_f32_e32 v137, v0
	v_sub_f32_e32 v0, v127, v94
	v_mul_f32_e32 v0, 0x3fb8aa3b, v0
	v_exp_f32_e32 v141, v0
	v_pk_mul_f32 v[20:21], v[20:21], v[136:137]
	v_bfe_u32 v0, v141, 16, 1
	v_add3_u32 v0, v141, v0, s89
	ds_write_b16_d16_hi v143, v0 offset:1568
	v_add_u32_e32 v0, s4, v80
	s_waitcnt lgkmcnt(0)
	s_barrier
	ds_read_b128 v[128:131], v0 offset:1024
	s_waitcnt vmcnt(8)
	v_cvt_pk_bf16_f32 v96, v69, v96
	v_cvt_pk_bf16_f32 v97, v97, v98
	v_cvt_pk_bf16_f32 v98, v99, v100
	v_cvt_pk_bf16_f32 v99, v101, v105
	v_pk_fma_f32 v[64:65], v[64:65], v[136:137], v[140:141]
	s_waitcnt lgkmcnt(0)
	v_mfma_f32_16x16x32_bf16 v[18:21], v[128:131], v[96:99], v[18:21]
	ds_read_b128 v[96:99], v0 offset:1088
	v_cvt_pk_bf16_f32 v100, v102, v103
	v_cvt_pk_bf16_f32 v101, v104, v106
	v_cvt_pk_bf16_f32 v102, v107, v108
	v_cvt_pk_bf16_f32 v103, v109, v111
	s_waitcnt lgkmcnt(0)
	v_mfma_f32_16x16x32_bf16 v[18:21], v[96:99], v[100:103], v[18:21]
	ds_read_b128 v[96:99], v0 offset:1152
	v_cvt_pk_bf16_f32 v100, v110, v112
	v_cvt_pk_bf16_f32 v101, v113, v114
	v_cvt_pk_bf16_f32 v102, v115, v116
	v_cvt_pk_bf16_f32 v103, v117, v122
	s_waitcnt lgkmcnt(0)
	v_mfma_f32_16x16x32_bf16 v[18:21], v[96:99], v[100:103], v[18:21]
	ds_read_b128 v[96:99], v0 offset:1216
	v_cvt_pk_bf16_f32 v100, v118, v119
	v_cvt_pk_bf16_f32 v101, v120, v121
	v_cvt_pk_bf16_f32 v102, v123, v124
	v_cvt_pk_bf16_f32 v103, v125, v126
	s_waitcnt lgkmcnt(0)
	v_mfma_f32_16x16x32_bf16 v[18:21], v[96:99], v[100:103], v[18:21]
	s_cbranch_scc1 .LBB0_1423
	v_mov_b32_e32 v0, v94
	v_mov_b32_e32 v94, v93
	v_mov_b32_e32 v93, v95
	v_mov_b32_e32 v95, v92
	s_branch .LBB0_1417
